# phase A convert: full-line stores now write-through (sc0 sc1)
# speedup vs baseline: 1.0210x; 1.0021x over previous
.LBB0_22:
	s_or_b64 exec, exec, s[28:29]
	v_mul_hi_u32_u24_e32 v17, v10, v2
	v_mul_u32_u24_e32 v16, v10, v2
	v_lshl_add_u64 v[8:9], v[16:17], 2, v[8:9]
	v_lshlrev_b32_e32 v16, 2, v0
	v_mov_b32_e32 v17, v3
	v_lshl_add_u64 v[8:9], v[8:9], 0, v[16:17]
	v_lshlrev_b64 v[10:11], 2, v[10:11]
	v_lshl_add_u64 v[16:17], v[8:9], 0, v[10:11]
	v_lshl_add_u64 v[18:19], v[16:17], 0, v[10:11]
	v_lshl_add_u64 v[20:21], v[18:19], 0, v[10:11]
	v_lshl_add_u64 v[22:23], v[20:21], 0, v[10:11]
	v_lshl_add_u64 v[24:25], v[22:23], 0, v[10:11]
	v_lshl_add_u64 v[26:27], v[24:25], 0, v[10:11]
	v_lshl_add_u64 v[28:29], v[26:27], 0, v[10:11]
	global_load_dword v30, v[8:9], off nt
	s_nop 0
	global_load_dword v16, v[16:17], off nt
	s_nop 0
	global_load_dword v17, v[18:19], off nt
	s_nop 0
	global_load_dword v18, v[20:21], off nt
	global_load_dword v19, v[22:23], off nt
	s_nop 0
	global_load_dword v20, v[24:25], off nt
	global_load_dword v21, v[26:27], off nt
	global_load_dword v22, v[28:29], off nt
	v_lshl_add_u64 v[8:9], v[28:29], 0, v[10:11]
	global_load_dword v23, v[8:9], off nt
	v_lshl_add_u64 v[8:9], v[8:9], 0, v[10:11]
	global_load_dword v24, v[8:9], off nt
	v_lshl_add_u64 v[8:9], v[8:9], 0, v[10:11]
	global_load_dword v25, v[8:9], off nt
	v_lshl_add_u64 v[8:9], v[8:9], 0, v[10:11]
	global_load_dword v26, v[8:9], off nt
	v_lshl_add_u64 v[8:9], v[8:9], 0, v[10:11]
	global_load_dword v27, v[8:9], off nt
	v_lshl_add_u64 v[8:9], v[8:9], 0, v[10:11]
	global_load_dword v28, v[8:9], off nt
	v_lshl_add_u64 v[8:9], v[8:9], 0, v[10:11]
	global_load_dword v29, v[8:9], off nt
	v_lshl_add_u64 v[8:9], v[8:9], 0, v[10:11]
	global_load_dword v31, v[8:9], off nt
	v_lshl_add_u64 v[8:9], v[8:9], 0, v[10:11]
	global_load_dword v32, v[8:9], off nt
	v_lshl_add_u64 v[8:9], v[8:9], 0, v[10:11]
	global_load_dword v33, v[8:9], off nt
	v_lshl_add_u64 v[8:9], v[8:9], 0, v[10:11]
	global_load_dword v34, v[8:9], off nt
	v_lshl_add_u64 v[8:9], v[8:9], 0, v[10:11]
	global_load_dword v35, v[8:9], off nt
	v_lshl_add_u64 v[8:9], v[8:9], 0, v[10:11]
	global_load_dword v36, v[8:9], off nt
	v_lshl_add_u64 v[8:9], v[8:9], 0, v[10:11]
	global_load_dword v37, v[8:9], off nt
	v_lshl_add_u64 v[8:9], v[8:9], 0, v[10:11]
	global_load_dword v38, v[8:9], off nt
	v_lshl_add_u64 v[8:9], v[8:9], 0, v[10:11]
	global_load_dword v39, v[8:9], off nt
	v_lshl_add_u64 v[8:9], v[8:9], 0, v[10:11]
	global_load_dword v40, v[8:9], off nt
	v_lshl_add_u64 v[8:9], v[8:9], 0, v[10:11]
	global_load_dword v41, v[8:9], off nt
	v_lshl_add_u64 v[8:9], v[8:9], 0, v[10:11]
	global_load_dword v42, v[8:9], off nt
	v_lshl_add_u64 v[8:9], v[8:9], 0, v[10:11]
	global_load_dword v43, v[8:9], off nt
	v_lshl_add_u64 v[8:9], v[8:9], 0, v[10:11]
	global_load_dword v44, v[8:9], off nt
	v_lshl_add_u64 v[8:9], v[8:9], 0, v[10:11]
	global_load_dword v45, v[8:9], off nt
	v_lshl_add_u64 v[8:9], v[8:9], 0, v[10:11]
	global_load_dword v46, v[8:9], off nt
	v_lshl_add_u64 v[8:9], v[8:9], 0, v[10:11]
	global_load_dword v47, v[8:9], off nt
	v_lshl_add_u64 v[8:9], v[8:9], 0, v[10:11]
	global_load_dword v48, v[8:9], off nt
	v_lshl_add_u64 v[8:9], v[8:9], 0, v[10:11]
	global_load_dword v49, v[8:9], off nt
	v_lshl_add_u64 v[8:9], v[8:9], 0, v[10:11]
	global_load_dword v50, v[8:9], off nt
	v_lshl_add_u64 v[8:9], v[8:9], 0, v[10:11]
	global_load_dword v51, v[8:9], off nt
	v_lshl_add_u64 v[8:9], v[8:9], 0, v[10:11]
	global_load_dword v52, v[8:9], off nt
	v_lshl_add_u64 v[8:9], v[8:9], 0, v[10:11]
	global_load_dword v53, v[8:9], off nt
	v_lshl_add_u64 v[8:9], v[8:9], 0, v[10:11]
	global_load_dword v54, v[8:9], off nt
	v_lshl_add_u64 v[8:9], v[8:9], 0, v[10:11]
	global_load_dword v55, v[8:9], off nt
	v_lshl_add_u64 v[8:9], v[8:9], 0, v[10:11]
	global_load_dword v56, v[8:9], off nt
	v_lshl_add_u64 v[8:9], v[8:9], 0, v[10:11]
	global_load_dword v57, v[8:9], off nt
	v_lshl_add_u64 v[8:9], v[8:9], 0, v[10:11]
	global_load_dword v58, v[8:9], off nt
	v_lshl_add_u64 v[8:9], v[8:9], 0, v[10:11]
	global_load_dword v59, v[8:9], off nt
	v_lshl_add_u64 v[8:9], v[8:9], 0, v[10:11]
	global_load_dword v60, v[8:9], off nt
	v_lshl_add_u64 v[8:9], v[8:9], 0, v[10:11]
	global_load_dword v61, v[8:9], off nt
	v_lshl_add_u64 v[8:9], v[8:9], 0, v[10:11]
	global_load_dword v62, v[8:9], off nt
	v_lshl_add_u64 v[8:9], v[8:9], 0, v[10:11]
	global_load_dword v63, v[8:9], off nt
	v_lshl_add_u64 v[8:9], v[8:9], 0, v[10:11]
	global_load_dword v64, v[8:9], off nt
	v_lshl_add_u64 v[8:9], v[8:9], 0, v[10:11]
	global_load_dword v65, v[8:9], off nt
	v_lshl_add_u64 v[8:9], v[8:9], 0, v[10:11]
	global_load_dword v66, v[8:9], off nt
	v_lshl_add_u64 v[8:9], v[8:9], 0, v[10:11]
	global_load_dword v67, v[8:9], off nt
	v_lshl_add_u64 v[8:9], v[8:9], 0, v[10:11]
	global_load_dword v68, v[8:9], off nt
	v_lshl_add_u64 v[8:9], v[8:9], 0, v[10:11]
	global_load_dword v69, v[8:9], off nt
	v_lshl_add_u64 v[8:9], v[8:9], 0, v[10:11]
	global_load_dword v70, v[8:9], off nt
	v_lshl_add_u64 v[8:9], v[8:9], 0, v[10:11]
	global_load_dword v71, v[8:9], off nt
	v_lshl_add_u64 v[8:9], v[8:9], 0, v[10:11]
	global_load_dword v72, v[8:9], off nt
	v_lshl_add_u64 v[8:9], v[8:9], 0, v[10:11]
	global_load_dword v73, v[8:9], off nt
	v_lshl_add_u64 v[8:9], v[8:9], 0, v[10:11]
	global_load_dword v74, v[8:9], off nt
	v_lshl_add_u64 v[8:9], v[8:9], 0, v[10:11]
	global_load_dword v75, v[8:9], off nt
	v_lshl_add_u64 v[8:9], v[8:9], 0, v[10:11]
	global_load_dword v76, v[8:9], off nt
	v_lshl_add_u64 v[8:9], v[8:9], 0, v[10:11]
	global_load_dword v77, v[8:9], off nt
	v_lshl_add_u64 v[8:9], v[8:9], 0, v[10:11]
	v_lshl_add_u64 v[10:11], v[8:9], 0, v[10:11]
	global_load_dword v78, v[8:9], off nt
	s_nop 0
	global_load_dword v10, v[10:11], off nt
	v_lshlrev_b32_e32 v126, 4, v6
	v_mul_u32_u24_e32 v6, v6, v128
	v_lshlrev_b32_e32 v6, 1, v6
	v_add_u32_e32 v6, v6, v129
	v_mov_b32_e32 v7, v3
	v_lshl_add_u64 v[8:9], v[4:5], 0, v[6:7]
	s_waitcnt vmcnt(62)
	v_cvt_pk_bf16_f32 v4, v30, v16
	s_waitcnt vmcnt(60)
	v_cvt_pk_bf16_f32 v5, v17, v18
	s_waitcnt vmcnt(58)
	v_cvt_pk_bf16_f32 v6, v19, v20
	s_waitcnt vmcnt(56)
	v_cvt_pk_bf16_f32 v7, v21, v22
	v_lshl_add_u64 v[8:9], v[2:3], 1, v[8:9]
	ds_write_b128 v86, v[4:7]
	v_add_u32_e32 v1, s84, v1
	s_movk_i32 s28, 0x2eff
	s_waitcnt vmcnt(54)
	v_cvt_pk_bf16_f32 v4, v23, v24
	s_waitcnt vmcnt(52)
	v_cvt_pk_bf16_f32 v5, v25, v26
	s_waitcnt vmcnt(50)
	v_cvt_pk_bf16_f32 v6, v27, v28
	s_waitcnt vmcnt(48)
	v_cvt_pk_bf16_f32 v7, v29, v31
	ds_write_b128 v87, v[4:7]
	v_cmp_lt_i32_e32 vcc, s28, v1
	v_add_u32_e32 v12, s2, v12
	s_waitcnt vmcnt(46)
	v_cvt_pk_bf16_f32 v4, v32, v33
	s_waitcnt vmcnt(44)
	v_cvt_pk_bf16_f32 v5, v34, v35
	s_waitcnt vmcnt(42)
	v_cvt_pk_bf16_f32 v6, v36, v37
	s_waitcnt vmcnt(40)
	v_cvt_pk_bf16_f32 v7, v38, v39
	ds_write_b128 v88, v[4:7]
	v_add_u32_e32 v13, s33, v13
	v_add_u32_e32 v14, s35, v14
	s_waitcnt vmcnt(38)
	v_cvt_pk_bf16_f32 v4, v40, v41
	s_waitcnt vmcnt(36)
	v_cvt_pk_bf16_f32 v5, v42, v43
	s_waitcnt vmcnt(34)
	v_cvt_pk_bf16_f32 v6, v44, v45
	s_waitcnt vmcnt(32)
	v_cvt_pk_bf16_f32 v7, v46, v47
	ds_write_b128 v89, v[4:7]
	s_or_b64 s[16:17], vcc, s[16:17]
	v_add_u32_e32 v15, s42, v15
	s_waitcnt vmcnt(30)
	v_cvt_pk_bf16_f32 v4, v48, v49
	s_waitcnt vmcnt(28)
	v_cvt_pk_bf16_f32 v5, v50, v51
	s_waitcnt vmcnt(26)
	v_cvt_pk_bf16_f32 v6, v52, v53
	s_waitcnt vmcnt(24)
	v_cvt_pk_bf16_f32 v7, v54, v55
	ds_write_b128 v90, v[4:7]
	s_waitcnt vmcnt(22)
	s_nop 0
	v_cvt_pk_bf16_f32 v4, v56, v57
	s_waitcnt vmcnt(20)
	v_cvt_pk_bf16_f32 v5, v58, v59
	s_waitcnt vmcnt(18)
	v_cvt_pk_bf16_f32 v6, v60, v61
	s_waitcnt vmcnt(16)
	v_cvt_pk_bf16_f32 v7, v62, v63
	ds_write_b128 v91, v[4:7]
	s_waitcnt vmcnt(14)
	s_nop 0
	v_cvt_pk_bf16_f32 v4, v64, v65
	s_waitcnt vmcnt(12)
	v_cvt_pk_bf16_f32 v5, v66, v67
	s_waitcnt vmcnt(10)
	v_cvt_pk_bf16_f32 v6, v68, v69
	s_waitcnt vmcnt(8)
	v_cvt_pk_bf16_f32 v7, v70, v71
	ds_write_b128 v92, v[4:7]
	s_waitcnt vmcnt(6)
	s_nop 0
	v_cvt_pk_bf16_f32 v4, v72, v73
	s_waitcnt vmcnt(4)
	v_cvt_pk_bf16_f32 v5, v74, v75
	s_waitcnt vmcnt(2)
	v_cvt_pk_bf16_f32 v6, v76, v77
	s_waitcnt vmcnt(0)
	v_cvt_pk_bf16_f32 v7, v78, v10
	ds_write_b128 v93, v[4:7]
	ds_read_b128 v[94:97], v132
	ds_read_b128 v[98:101], v132 offset:1024
	ds_read_b128 v[102:105], v132 offset:2048
	ds_read_b128 v[106:109], v132 offset:3072
	ds_read_b128 v[110:113], v132 offset:4096
	ds_read_b128 v[114:117], v132 offset:5120
	ds_read_b128 v[118:121], v132 offset:6144
	ds_read_b128 v[122:125], v132 offset:7168
	s_waitcnt lgkmcnt(7)
	global_store_dwordx4 v[8:9], v[94:97], off sc0 sc1
	v_lshl_add_u64 v[8:9], v[8:9], 0, v[126:127]
	s_waitcnt lgkmcnt(6)
	global_store_dwordx4 v[8:9], v[98:101], off sc0 sc1
	v_lshl_add_u64 v[8:9], v[8:9], 0, v[126:127]
	s_waitcnt lgkmcnt(5)
	global_store_dwordx4 v[8:9], v[102:105], off sc0 sc1
	v_lshl_add_u64 v[8:9], v[8:9], 0, v[126:127]
	s_waitcnt lgkmcnt(4)
	global_store_dwordx4 v[8:9], v[106:109], off sc0 sc1
	v_lshl_add_u64 v[8:9], v[8:9], 0, v[126:127]
	s_waitcnt lgkmcnt(3)
	global_store_dwordx4 v[8:9], v[110:113], off sc0 sc1
	v_lshl_add_u64 v[8:9], v[8:9], 0, v[126:127]
	s_waitcnt lgkmcnt(2)
	global_store_dwordx4 v[8:9], v[114:117], off sc0 sc1
	v_lshl_add_u64 v[8:9], v[8:9], 0, v[126:127]
	s_waitcnt lgkmcnt(1)
	global_store_dwordx4 v[8:9], v[118:121], off sc0 sc1
	v_lshl_add_u64 v[8:9], v[8:9], 0, v[126:127]
	s_waitcnt lgkmcnt(0)
	global_store_dwordx4 v[8:9], v[122:125], off sc0 sc1
	s_andn2_b64 exec, exec, s[16:17]
	s_cbranch_execz .LBB0_39
